# first seam: the arrive is issued before the XCD census loads so both share one round trip
# baseline (speedup 1.0000x reference)
.LBB0_112:
	s_waitcnt vmcnt(0)
	s_barrier
	s_mov_b64 s[0:1], exec
	v_readlane_b32 s2, v252, 9
	v_readlane_b32 s3, v252, 10
	s_and_b64 s[2:3], s[0:1], s[2:3]
	s_mov_b64 exec, s[2:3]
	s_cbranch_execz .LBB0_164
	v_readlane_b32 s30, v252, 11
	v_readlane_b32 s31, v252, 12
	v_readlane_b32 s32, v252, 13
	v_mov_b32_e32 v5, 1
	v_mov_b32_e32 v22, 0
	s_add_u32 s34, s30, 0x1400
	s_addc_u32 s35, s31, 0
	s_lshl_b32 s32, s32, 8
	s_add_u32 s40, s30, 0x3400
	s_addc_u32 s41, s31, 0
	v_mov_b32_e32 v4, s32
	s_mov_b32 s42, 0
	global_atomic_add v29, v4, v5, s[34:35] sc0
	buffer_inv sc1
	s_add_u32 s36, s30, 0x400
	s_addc_u32 s37, s31, 0

.Lxb1_census_done:
	v_readfirstlane_b32 s98, v28
	s_mov_b32 s42, 0
	s_mul_i32 s33, s86, 1
	s_mul_i32 s39, s98, 1
	s_waitcnt vmcnt(0)
	v_readfirstlane_b32 s38, v29
	v_mov_b32_e32 v7, s98
	s_add_i32 s38, s38, 1
	s_cmp_lg_u32 s38, s39
	s_cbranch_scc1 .Lxb1_spin
	buffer_wbl2 sc1
	s_waitcnt vmcnt(0)
	global_atomic_add v22, v7, s[40:41]
